# first K-loop body peeled: first MFMA per accumulator block takes C=0 instead of 128 v_mov zero fills per tile
# speedup vs baseline: 1.0483x; 1.0053x over previous
.Llora_n:
	s_add_u32 s10, s78, 0x80
	s_addc_u32 s11, s79, 0
	s_add_u32 s84, s84, 0x100
	s_addc_u32 s85, s85, 0
	s_mov_b32 s78, 0
	s_add_i32 s72, s78, 2
	s_add_u32 s79, s10, 0x80
	s_addc_u32 vcc_lo, s11, 0
	v_add_u32_e32 v148, 0x10000, v185
	s_cmp_eq_u32 s15, s78
	s_cselect_b32 s78, s12, s84
	s_cselect_b32 vcc_hi, s49, vcc_lo
	s_cselect_b32 vcc_lo, s48, s79
	s_cselect_b32 s79, s13, s85
	ds_read_b128 v[128:131], v148 offset:0
	ds_read_b128 v[132:135], v148 offset:1024
	ds_read_b128 v[136:139], v148 offset:2048
	ds_read_b128 v[140:143], v148 offset:3072
	ds_read_b128 v[218:221], v148 offset:16384
	ds_read_b128 v[222:225], v148 offset:17408
	ds_read_b128 v[226:229], v148 offset:18432
	ds_read_b128 v[230:233], v148 offset:19456
	ds_read_b128 v[162:165], v188 offset:0
	ds_read_b128 v[190:193], v188 offset:1024
	ds_read_b128 v[194:197], v188 offset:2048
	ds_read_b128 v[198:201], v188 offset:3072
	ds_read_b128 v[202:205], v188 offset:4096
	ds_read_b128 v[206:209], v188 offset:5120
	ds_read_b128 v[210:213], v188 offset:6144
	ds_read_b128 v[214:217], v188 offset:7168
	s_add_u32 s4, s10, s26
	s_addc_u32 s5, s11, 0
	s_add_i32 m0, s81, 0xc000
	s_nop 0
	global_load_lds_dwordx4 v152, s[4:5]
	s_add_i32 m0, s81, 0xe000
	s_nop 0
	global_load_lds_dwordx4 v144, s[4:5]
	s_waitcnt vmcnt(8)
	s_waitcnt lgkmcnt(0)
	s_barrier
	s_setprio 1
	v_mfma_f32_16x16x32_bf16 v[124:127], v[128:131], v[162:165], 0
	v_mfma_f32_16x16x32_bf16 v[116:119], v[136:139], v[162:165], 0
	v_mfma_f32_16x16x32_bf16 v[120:123], v[128:131], v[194:197], 0
	v_mfma_f32_16x16x32_bf16 v[112:115], v[136:139], v[194:197], 0
	v_mfma_f32_16x16x32_bf16 v[92:95], v[128:131], v[202:205], 0
	v_mfma_f32_16x16x32_bf16 v[84:87], v[136:139], v[202:205], 0
	v_mfma_f32_16x16x32_bf16 v[88:91], v[128:131], v[210:213], 0
	v_mfma_f32_16x16x32_bf16 v[80:83], v[136:139], v[210:213], 0
	v_mfma_f32_16x16x32_bf16 v[124:127], v[132:135], v[190:193], v[124:127]
	v_mfma_f32_16x16x32_bf16 v[116:119], v[140:143], v[190:193], v[116:119]
	v_mfma_f32_16x16x32_bf16 v[120:123], v[132:135], v[198:201], v[120:123]
	v_mfma_f32_16x16x32_bf16 v[112:115], v[140:143], v[198:201], v[112:115]
	v_mfma_f32_16x16x32_bf16 v[92:95], v[132:135], v[206:209], v[92:95]
	v_mfma_f32_16x16x32_bf16 v[84:87], v[140:143], v[206:209], v[84:87]
	v_mfma_f32_16x16x32_bf16 v[88:91], v[132:135], v[214:217], v[88:91]
	v_mfma_f32_16x16x32_bf16 v[80:83], v[140:143], v[214:217], v[80:83]
	v_mfma_f32_16x16x32_bf16 v[108:111], v[218:221], v[162:165], 0
	v_mfma_f32_16x16x32_bf16 v[100:103], v[226:229], v[162:165], 0
	v_mfma_f32_16x16x32_bf16 v[104:107], v[218:221], v[194:197], 0
	v_mfma_f32_16x16x32_bf16 v[96:99], v[226:229], v[194:197], 0
	v_mfma_f32_16x16x32_bf16 v[76:79], v[218:221], v[202:205], 0
	v_mfma_f32_16x16x32_bf16 v[68:71], v[226:229], v[202:205], 0
	v_mfma_f32_16x16x32_bf16 v[72:75], v[218:221], v[210:213], 0
	v_mfma_f32_16x16x32_bf16 v[64:67], v[226:229], v[210:213], 0
	v_mfma_f32_16x16x32_bf16 v[108:111], v[222:225], v[190:193], v[108:111]
	v_mfma_f32_16x16x32_bf16 v[100:103], v[230:233], v[190:193], v[100:103]
	v_mfma_f32_16x16x32_bf16 v[104:107], v[222:225], v[198:201], v[104:107]
	v_mfma_f32_16x16x32_bf16 v[96:99], v[230:233], v[198:201], v[96:99]
	v_mfma_f32_16x16x32_bf16 v[76:79], v[222:225], v[206:209], v[76:79]
	v_mfma_f32_16x16x32_bf16 v[68:71], v[230:233], v[206:209], v[68:71]
	v_mfma_f32_16x16x32_bf16 v[72:75], v[222:225], v[214:217], v[72:75]
	v_mfma_f32_16x16x32_bf16 v[64:67], v[230:233], v[214:217], v[64:67]
	s_setprio 0
	s_barrier
	ds_read_b128 v[162:165], v188 offset:16384
	ds_read_b128 v[190:193], v188 offset:17408
	ds_read_b128 v[194:197], v188 offset:18432
	ds_read_b128 v[198:201], v188 offset:19456
	ds_read_b128 v[202:205], v188 offset:20480
	ds_read_b128 v[206:209], v188 offset:21504
	ds_read_b128 v[210:213], v188 offset:22528
	ds_read_b128 v[214:217], v188 offset:23552
	s_add_i32 m0, s81, 0x10000
	s_nop 0
	global_load_lds_dwordx4 v154, s[78:79]
	s_add_i32 m0, s81, 0x12000
	s_nop 0
	global_load_lds_dwordx4 v146, s[78:79]
	s_add_i32 m0, s81, 0x0
	s_nop 0
	global_load_lds_dwordx4 v152, vcc
	s_add_i32 m0, s81, 0x2000
	s_nop 0
	global_load_lds_dwordx4 v144, vcc
	s_add_u32 s4, s78, s26
	s_addc_u32 s5, s79, 0
	s_add_i32 m0, s81, 0x14000
	s_nop 0
	global_load_lds_dwordx4 v154, s[4:5]
	s_add_i32 m0, s81, 0x16000
	s_nop 0
	global_load_lds_dwordx4 v146, s[4:5]
	s_waitcnt vmcnt(8)
	s_waitcnt lgkmcnt(0)
	s_barrier
	s_setprio 1
	v_mfma_f32_16x16x32_bf16 v[60:63], v[128:131], v[162:165], 0
	v_mfma_f32_16x16x32_bf16 v[56:59], v[136:139], v[162:165], 0
	v_mfma_f32_16x16x32_bf16 v[52:55], v[128:131], v[194:197], 0
	v_mfma_f32_16x16x32_bf16 v[48:51], v[136:139], v[194:197], 0
	v_mfma_f32_16x16x32_bf16 v[28:31], v[128:131], v[202:205], 0
	v_mfma_f32_16x16x32_bf16 v[20:23], v[136:139], v[202:205], 0
	v_mfma_f32_16x16x32_bf16 v[24:27], v[128:131], v[210:213], 0
	v_mfma_f32_16x16x32_bf16 v[16:19], v[136:139], v[210:213], 0
	v_mfma_f32_16x16x32_bf16 v[60:63], v[132:135], v[190:193], v[60:63]
	v_mfma_f32_16x16x32_bf16 v[56:59], v[140:143], v[190:193], v[56:59]
	v_mfma_f32_16x16x32_bf16 v[52:55], v[132:135], v[198:201], v[52:55]
	v_mfma_f32_16x16x32_bf16 v[48:51], v[140:143], v[198:201], v[48:51]
	v_mfma_f32_16x16x32_bf16 v[28:31], v[132:135], v[206:209], v[28:31]
	v_mfma_f32_16x16x32_bf16 v[20:23], v[140:143], v[206:209], v[20:23]
	v_mfma_f32_16x16x32_bf16 v[24:27], v[132:135], v[214:217], v[24:27]
	v_mfma_f32_16x16x32_bf16 v[16:19], v[140:143], v[214:217], v[16:19]
	v_mfma_f32_16x16x32_bf16 v[44:47], v[218:221], v[162:165], 0
	v_mfma_f32_16x16x32_bf16 v[36:39], v[226:229], v[162:165], 0
	v_mfma_f32_16x16x32_bf16 v[40:43], v[218:221], v[194:197], 0
	v_mfma_f32_16x16x32_bf16 v[32:35], v[226:229], v[194:197], 0
	v_mfma_f32_16x16x32_bf16 v[12:15], v[218:221], v[202:205], 0
	v_mfma_f32_16x16x32_bf16 v[4:7], v[226:229], v[202:205], 0
	v_mfma_f32_16x16x32_bf16 v[8:11], v[218:221], v[210:213], 0
	v_mfma_f32_16x16x32_bf16 v[0:3], v[226:229], v[210:213], 0
	v_mfma_f32_16x16x32_bf16 v[44:47], v[222:225], v[190:193], v[44:47]
	v_mfma_f32_16x16x32_bf16 v[36:39], v[230:233], v[190:193], v[36:39]
	v_mfma_f32_16x16x32_bf16 v[40:43], v[222:225], v[198:201], v[40:43]
	v_mfma_f32_16x16x32_bf16 v[32:35], v[230:233], v[198:201], v[32:35]
	v_mfma_f32_16x16x32_bf16 v[12:15], v[222:225], v[206:209], v[12:15]
	v_mfma_f32_16x16x32_bf16 v[4:7], v[230:233], v[206:209], v[4:7]
	v_mfma_f32_16x16x32_bf16 v[8:11], v[222:225], v[214:217], v[8:11]
	v_mfma_f32_16x16x32_bf16 v[0:3], v[230:233], v[214:217], v[0:3]
	s_setprio 0
	s_barrier
	ds_read_b128 v[128:131], v148 offset:32768
	ds_read_b128 v[132:135], v148 offset:33792
	ds_read_b128 v[136:139], v148 offset:34816
	ds_read_b128 v[140:143], v148 offset:35840
	ds_read_b128 v[218:221], v148 offset:49152
	ds_read_b128 v[222:225], v148 offset:50176
	ds_read_b128 v[226:229], v148 offset:51200
	ds_read_b128 v[230:233], v148 offset:52224
	ds_read_b128 v[162:165], v188 offset:32768
	ds_read_b128 v[190:193], v188 offset:33792
	ds_read_b128 v[194:197], v188 offset:34816
	ds_read_b128 v[198:201], v188 offset:35840
	ds_read_b128 v[202:205], v188 offset:36864
	ds_read_b128 v[206:209], v188 offset:37888
	ds_read_b128 v[210:213], v188 offset:38912
	ds_read_b128 v[214:217], v188 offset:39936
	s_add_u32 s4, vcc_lo, s26
	s_addc_u32 s5, vcc_hi, 0
	s_add_i32 m0, s81, 0x4000
	s_nop 0
	global_load_lds_dwordx4 v152, s[4:5]
	s_add_i32 m0, s81, 0x6000
	s_nop 0
	global_load_lds_dwordx4 v144, s[4:5]
	s_waitcnt vmcnt(8)
	s_waitcnt lgkmcnt(0)
	s_barrier
	s_setprio 1
	v_mfma_f32_16x16x32_bf16 v[124:127], v[128:131], v[162:165], v[124:127]
	v_mfma_f32_16x16x32_bf16 v[116:119], v[136:139], v[162:165], v[116:119]
	v_mfma_f32_16x16x32_bf16 v[120:123], v[128:131], v[194:197], v[120:123]
	v_mfma_f32_16x16x32_bf16 v[112:115], v[136:139], v[194:197], v[112:115]
	v_mfma_f32_16x16x32_bf16 v[92:95], v[128:131], v[202:205], v[92:95]
	v_mfma_f32_16x16x32_bf16 v[84:87], v[136:139], v[202:205], v[84:87]
	v_mfma_f32_16x16x32_bf16 v[88:91], v[128:131], v[210:213], v[88:91]
	v_mfma_f32_16x16x32_bf16 v[80:83], v[136:139], v[210:213], v[80:83]
	v_mfma_f32_16x16x32_bf16 v[124:127], v[132:135], v[190:193], v[124:127]
	v_mfma_f32_16x16x32_bf16 v[116:119], v[140:143], v[190:193], v[116:119]
	v_mfma_f32_16x16x32_bf16 v[120:123], v[132:135], v[198:201], v[120:123]
	v_mfma_f32_16x16x32_bf16 v[112:115], v[140:143], v[198:201], v[112:115]
	v_mfma_f32_16x16x32_bf16 v[92:95], v[132:135], v[206:209], v[92:95]
	v_mfma_f32_16x16x32_bf16 v[84:87], v[140:143], v[206:209], v[84:87]
	v_mfma_f32_16x16x32_bf16 v[88:91], v[132:135], v[214:217], v[88:91]
	v_mfma_f32_16x16x32_bf16 v[80:83], v[140:143], v[214:217], v[80:83]
	v_mfma_f32_16x16x32_bf16 v[108:111], v[218:221], v[162:165], v[108:111]
	v_mfma_f32_16x16x32_bf16 v[100:103], v[226:229], v[162:165], v[100:103]
	v_mfma_f32_16x16x32_bf16 v[104:107], v[218:221], v[194:197], v[104:107]
	v_mfma_f32_16x16x32_bf16 v[96:99], v[226:229], v[194:197], v[96:99]
	v_mfma_f32_16x16x32_bf16 v[76:79], v[218:221], v[202:205], v[76:79]
	v_mfma_f32_16x16x32_bf16 v[68:71], v[226:229], v[202:205], v[68:71]
	v_mfma_f32_16x16x32_bf16 v[72:75], v[218:221], v[210:213], v[72:75]
	v_mfma_f32_16x16x32_bf16 v[64:67], v[226:229], v[210:213], v[64:67]
	v_mfma_f32_16x16x32_bf16 v[108:111], v[222:225], v[190:193], v[108:111]
	v_mfma_f32_16x16x32_bf16 v[100:103], v[230:233], v[190:193], v[100:103]
	v_mfma_f32_16x16x32_bf16 v[104:107], v[222:225], v[198:201], v[104:107]
	v_mfma_f32_16x16x32_bf16 v[96:99], v[230:233], v[198:201], v[96:99]
	v_mfma_f32_16x16x32_bf16 v[76:79], v[222:225], v[206:209], v[76:79]
	v_mfma_f32_16x16x32_bf16 v[68:71], v[230:233], v[206:209], v[68:71]
	v_mfma_f32_16x16x32_bf16 v[72:75], v[222:225], v[214:217], v[72:75]
	v_mfma_f32_16x16x32_bf16 v[64:67], v[230:233], v[214:217], v[64:67]
	s_setprio 0
	s_barrier
	ds_read_b128 v[162:165], v188 offset:49152
	ds_read_b128 v[190:193], v188 offset:50176
	ds_read_b128 v[194:197], v188 offset:51200
	ds_read_b128 v[198:201], v188 offset:52224
	ds_read_b128 v[202:205], v188 offset:53248
	ds_read_b128 v[206:209], v188 offset:54272
	ds_read_b128 v[210:213], v188 offset:55296
	ds_read_b128 v[214:217], v188 offset:56320
	s_add_u32 s4, s78, 0x80
	s_addc_u32 s5, s79, 0
	s_add_i32 m0, s81, 0x18000
	s_nop 0
	global_load_lds_dwordx4 v154, s[4:5]
	s_add_i32 m0, s81, 0x1a000
	s_nop 0
	global_load_lds_dwordx4 v146, s[4:5]
	s_add_u32 s4, vcc_lo, 0x80
	s_addc_u32 s5, vcc_hi, 0
	s_add_i32 m0, s81, 0x8000
	s_nop 0
	global_load_lds_dwordx4 v152, s[4:5]
	s_add_i32 m0, s81, 0xa000
	s_nop 0
	global_load_lds_dwordx4 v144, s[4:5]
	s_add_u32 s4, s78, s26
	s_addc_u32 s5, s79, 0
	s_add_u32 s4, s4, 0x80
	s_addc_u32 s5, s5, 0
	s_add_i32 m0, s81, 0x1c000
	s_nop 0
	global_load_lds_dwordx4 v154, s[4:5]
	s_add_i32 m0, s81, 0x1e000
	s_nop 0
	global_load_lds_dwordx4 v146, s[4:5]
	s_waitcnt vmcnt(8)
	s_waitcnt lgkmcnt(0)
	s_barrier
	s_setprio 1
	v_mfma_f32_16x16x32_bf16 v[60:63], v[128:131], v[162:165], v[60:63]
	v_mfma_f32_16x16x32_bf16 v[56:59], v[136:139], v[162:165], v[56:59]
	v_mfma_f32_16x16x32_bf16 v[52:55], v[128:131], v[194:197], v[52:55]
	v_mfma_f32_16x16x32_bf16 v[48:51], v[136:139], v[194:197], v[48:51]
	v_mfma_f32_16x16x32_bf16 v[28:31], v[128:131], v[202:205], v[28:31]
	v_mfma_f32_16x16x32_bf16 v[20:23], v[136:139], v[202:205], v[20:23]
	v_mfma_f32_16x16x32_bf16 v[24:27], v[128:131], v[210:213], v[24:27]
	v_mfma_f32_16x16x32_bf16 v[16:19], v[136:139], v[210:213], v[16:19]
	v_mfma_f32_16x16x32_bf16 v[60:63], v[132:135], v[190:193], v[60:63]
	v_mfma_f32_16x16x32_bf16 v[56:59], v[140:143], v[190:193], v[56:59]
	v_mfma_f32_16x16x32_bf16 v[52:55], v[132:135], v[198:201], v[52:55]
	v_mfma_f32_16x16x32_bf16 v[48:51], v[140:143], v[198:201], v[48:51]
	v_mfma_f32_16x16x32_bf16 v[28:31], v[132:135], v[206:209], v[28:31]
	v_mfma_f32_16x16x32_bf16 v[20:23], v[140:143], v[206:209], v[20:23]
	v_mfma_f32_16x16x32_bf16 v[24:27], v[132:135], v[214:217], v[24:27]
	v_mfma_f32_16x16x32_bf16 v[16:19], v[140:143], v[214:217], v[16:19]
	v_mfma_f32_16x16x32_bf16 v[44:47], v[218:221], v[162:165], v[44:47]
	v_mfma_f32_16x16x32_bf16 v[36:39], v[226:229], v[162:165], v[36:39]
	v_mfma_f32_16x16x32_bf16 v[40:43], v[218:221], v[194:197], v[40:43]
	v_mfma_f32_16x16x32_bf16 v[32:35], v[226:229], v[194:197], v[32:35]
	v_mfma_f32_16x16x32_bf16 v[12:15], v[218:221], v[202:205], v[12:15]
	v_mfma_f32_16x16x32_bf16 v[4:7], v[226:229], v[202:205], v[4:7]
	v_mfma_f32_16x16x32_bf16 v[8:11], v[218:221], v[210:213], v[8:11]
	v_mfma_f32_16x16x32_bf16 v[0:3], v[226:229], v[210:213], v[0:3]
	v_mfma_f32_16x16x32_bf16 v[44:47], v[222:225], v[190:193], v[44:47]
	v_mfma_f32_16x16x32_bf16 v[36:39], v[230:233], v[190:193], v[36:39]
	v_mfma_f32_16x16x32_bf16 v[40:43], v[222:225], v[198:201], v[40:43]
	v_mfma_f32_16x16x32_bf16 v[32:35], v[230:233], v[198:201], v[32:35]
	v_mfma_f32_16x16x32_bf16 v[12:15], v[222:225], v[206:209], v[12:15]
	v_mfma_f32_16x16x32_bf16 v[4:7], v[230:233], v[206:209], v[4:7]
	v_mfma_f32_16x16x32_bf16 v[8:11], v[222:225], v[214:217], v[8:11]
	v_mfma_f32_16x16x32_bf16 v[0:3], v[230:233], v[214:217], v[0:3]
	s_setprio 0
	s_add_u32 s10, s10, 0x100
	s_addc_u32 s11, s11, 0
	s_add_u32 s84, s84, 0x100
	s_addc_u32 s85, s85, 0
	s_cmp_ge_u32 s72, s76
	s_mov_b32 s78, s72
	s_barrier
	s_cbranch_scc1 .Lkloop_done

.Lkloop_done:
	v_lshl_add_u32 v162, s20, 8, v151
	s_cmp_lt_i32 s45, 2
	s_mov_b64 s[10:11], -1
	s_cbranch_scc1 .LBB0_537
	s_cmp_gt_i32 s45, 2
	s_cbranch_scc0 .LBB0_534
	s_add_i32 s10, s25, 2
	s_cmp_gt_u32 s10, 4
	s_mov_b64 s[10:11], -1
	s_cbranch_scc0 .LBB0_531
	s_add_i32 s10, s25, -3
	s_cmp_gt_u32 s10, 2
	v_lshl_or_b32 v148, s25, 8, v186
	s_mov_b64 s[10:11], -1
	s_cbranch_scc0 .LBB0_528
	v_ashrrev_i32_e32 v128, 31, v162
	v_mul_lo_u32 v134, s29, v162
	v_mul_lo_u32 v136, s28, v128
	v_mad_u64_u32 v[128:129], s[10:11], s28, v162, 0
	v_add3_u32 v129, v129, v136, v134
	v_lshl_add_u64 v[134:135], v[128:129], 1, s[70:71]
	v_ashrrev_i32_e32 v129, 31, v148
	v_mov_b32_e32 v128, v148
	v_lshlrev_b64 v[128:129], 1, v[128:129]
	v_cvt_pk_bf16_f32 v130, v124, v125
	v_cvt_pk_bf16_f32 v131, v126, v127
	v_cvt_pk_bf16_f32 v132, v116, v117
	v_cvt_pk_bf16_f32 v133, v118, v119
	v_lshl_add_u64 v[134:135], v[134:135], 0, v[128:129]
	global_store_dwordx4 v[134:135], v[130:133], off nt
	s_nop 1
	v_cvt_pk_bf16_f32 v130, v108, v109
	v_cvt_pk_bf16_f32 v131, v110, v111
	v_cvt_pk_bf16_f32 v132, v100, v101
	v_cvt_pk_bf16_f32 v133, v102, v103
	global_store_dwordx4 v[134:135], v[130:133], off offset:256 nt
	v_or_b32_e32 v134, 16, v162
	v_mul_lo_u32 v137, s29, v134
	v_mad_u64_u32 v[134:135], s[10:11], s28, v134, 0
	v_add3_u32 v135, v135, v136, v137
	v_lshl_add_u64 v[134:135], v[134:135], 1, s[70:71]
	v_cvt_pk_bf16_f32 v130, v120, v121
	v_cvt_pk_bf16_f32 v131, v122, v123
	v_cvt_pk_bf16_f32 v132, v112, v113
	v_cvt_pk_bf16_f32 v133, v114, v115
	v_lshl_add_u64 v[134:135], v[134:135], 0, v[128:129]
	global_store_dwordx4 v[134:135], v[130:133], off nt
	s_nop 1
	v_cvt_pk_bf16_f32 v130, v104, v105
	v_cvt_pk_bf16_f32 v131, v106, v107
	v_cvt_pk_bf16_f32 v132, v96, v97
	v_cvt_pk_bf16_f32 v133, v98, v99
	global_store_dwordx4 v[134:135], v[130:133], off offset:256 nt
	v_or_b32_e32 v134, 32, v162
	v_mul_lo_u32 v137, s29, v134
	v_mad_u64_u32 v[134:135], s[10:11], s28, v134, 0
	v_add3_u32 v135, v135, v136, v137
	v_lshl_add_u64 v[134:135], v[134:135], 1, s[70:71]
	v_cvt_pk_bf16_f32 v130, v92, v93
	v_cvt_pk_bf16_f32 v131, v94, v95
	v_cvt_pk_bf16_f32 v132, v84, v85
	v_cvt_pk_bf16_f32 v133, v86, v87
	v_lshl_add_u64 v[134:135], v[134:135], 0, v[128:129]
	global_store_dwordx4 v[134:135], v[130:133], off nt
	s_nop 1
	v_cvt_pk_bf16_f32 v130, v76, v77
	v_cvt_pk_bf16_f32 v131, v78, v79
	v_cvt_pk_bf16_f32 v132, v68, v69
	v_cvt_pk_bf16_f32 v133, v70, v71
	global_store_dwordx4 v[134:135], v[130:133], off offset:256 nt
	v_or_b32_e32 v134, 48, v162
	v_mul_lo_u32 v137, s29, v134
	v_mad_u64_u32 v[134:135], s[10:11], s28, v134, 0
	v_add3_u32 v135, v135, v136, v137
	v_lshl_add_u64 v[134:135], v[134:135], 1, s[70:71]
	v_cvt_pk_bf16_f32 v130, v88, v89
	v_cvt_pk_bf16_f32 v131, v90, v91
	v_cvt_pk_bf16_f32 v132, v80, v81
	v_cvt_pk_bf16_f32 v133, v82, v83
	v_lshl_add_u64 v[134:135], v[134:135], 0, v[128:129]
	global_store_dwordx4 v[134:135], v[130:133], off nt
	s_nop 1
	v_cvt_pk_bf16_f32 v130, v72, v73
	v_cvt_pk_bf16_f32 v131, v74, v75
	v_cvt_pk_bf16_f32 v132, v64, v65
	v_cvt_pk_bf16_f32 v133, v66, v67
	global_store_dwordx4 v[134:135], v[130:133], off offset:256 nt
	v_add_u32_e32 v134, 0x80, v162
	v_ashrrev_i32_e32 v135, 31, v134
	v_mul_lo_u32 v136, s28, v135
	v_mul_lo_u32 v137, s29, v134
	v_mad_u64_u32 v[134:135], s[10:11], s28, v134, 0
	v_add3_u32 v135, v135, v136, v137
	v_lshl_add_u64 v[134:135], v[134:135], 1, s[70:71]
	v_cvt_pk_bf16_f32 v130, v60, v61
	v_cvt_pk_bf16_f32 v131, v62, v63
	v_cvt_pk_bf16_f32 v132, v56, v57
	v_cvt_pk_bf16_f32 v133, v58, v59
	v_lshl_add_u64 v[134:135], v[134:135], 0, v[128:129]
	global_store_dwordx4 v[134:135], v[130:133], off nt
	s_nop 1
	v_cvt_pk_bf16_f32 v130, v44, v45
	v_cvt_pk_bf16_f32 v131, v46, v47
	v_cvt_pk_bf16_f32 v132, v36, v37
	v_cvt_pk_bf16_f32 v133, v38, v39
	global_store_dwordx4 v[134:135], v[130:133], off offset:256 nt
	v_add_u32_e32 v134, 0x90, v162
	v_ashrrev_i32_e32 v135, 31, v134
	v_mul_lo_u32 v136, s28, v135
	v_mul_lo_u32 v137, s29, v134
	v_mad_u64_u32 v[134:135], s[10:11], s28, v134, 0
	v_add3_u32 v135, v135, v136, v137
	v_lshl_add_u64 v[134:135], v[134:135], 1, s[70:71]
	v_cvt_pk_bf16_f32 v130, v52, v53
	v_cvt_pk_bf16_f32 v131, v54, v55
	v_cvt_pk_bf16_f32 v132, v48, v49
	v_cvt_pk_bf16_f32 v133, v50, v51
	v_lshl_add_u64 v[134:135], v[134:135], 0, v[128:129]
	global_store_dwordx4 v[134:135], v[130:133], off nt
	s_nop 1
	v_cvt_pk_bf16_f32 v130, v40, v41
	v_cvt_pk_bf16_f32 v131, v42, v43
	v_cvt_pk_bf16_f32 v132, v32, v33
	v_cvt_pk_bf16_f32 v133, v34, v35
	global_store_dwordx4 v[134:135], v[130:133], off offset:256 nt
	v_add_u32_e32 v134, 0xa0, v162
	v_ashrrev_i32_e32 v135, 31, v134
	v_mul_lo_u32 v136, s28, v135
	v_mul_lo_u32 v137, s29, v134
	v_mad_u64_u32 v[134:135], s[10:11], s28, v134, 0
	v_add3_u32 v135, v135, v136, v137
	v_lshl_add_u64 v[134:135], v[134:135], 1, s[70:71]
	v_cvt_pk_bf16_f32 v130, v28, v29
	v_cvt_pk_bf16_f32 v131, v30, v31
	v_cvt_pk_bf16_f32 v132, v20, v21
	v_cvt_pk_bf16_f32 v133, v22, v23
	v_lshl_add_u64 v[134:135], v[134:135], 0, v[128:129]
	global_store_dwordx4 v[134:135], v[130:133], off nt
	s_nop 1
	v_cvt_pk_bf16_f32 v130, v12, v13
	v_cvt_pk_bf16_f32 v131, v14, v15
	v_cvt_pk_bf16_f32 v132, v4, v5
	v_cvt_pk_bf16_f32 v133, v6, v7
	global_store_dwordx4 v[134:135], v[130:133], off offset:256 nt
	v_add_u32_e32 v134, 0xb0, v162
	v_ashrrev_i32_e32 v135, 31, v134
	v_mul_lo_u32 v136, s28, v135
	v_mul_lo_u32 v137, s29, v134
	v_mad_u64_u32 v[134:135], s[10:11], s28, v134, 0
	v_add3_u32 v135, v135, v136, v137
	v_lshl_add_u64 v[134:135], v[134:135], 1, s[70:71]
	v_cvt_pk_bf16_f32 v130, v24, v25
	v_cvt_pk_bf16_f32 v131, v26, v27
	v_lshl_add_u64 v[134:135], v[134:135], 0, v[128:129]
	v_cvt_pk_bf16_f32 v132, v16, v17
	v_cvt_pk_bf16_f32 v133, v18, v19
	global_store_dwordx4 v[134:135], v[130:133], off nt
	v_cvt_pk_bf16_f32 v128, v8, v9
	v_cvt_pk_bf16_f32 v129, v10, v11
	s_mov_b64 s[10:11], 0
	s_nop 0
	v_cvt_pk_bf16_f32 v130, v0, v1
	v_cvt_pk_bf16_f32 v131, v2, v3
	global_store_dwordx4 v[134:135], v[128:131], off offset:256 nt
